# p7 pull samples a chains-done word (own cache line) together with the ticket and skips the per-series flag poll when all chains are done
# speedup vs baseline: 1.0005x; 1.0005x over previous
.Lchain_pub:
	s_waitcnt vmcnt(0)
	s_barrier
	s_and_saveexec_b64 s[98:99], s[44:45]
	s_cbranch_execz .Lchain_pub_done
	buffer_wbl2 sc1
	s_waitcnt vmcnt(0)
	s_lshr_b32 s100, s54, 5
	s_lshl_b32 s100, s100, 1
	s_bfe_u32 s101, s54, 0x10002
	s_add_i32 s100, s100, s101
	s_lshl_b32 s100, s100, 8
	s_add_i32 s100, s100, 0x800
	v_mov_b32_e32 v250, s100
	v_mov_b32_e32 v251, 1
	global_atomic_add v250, v251, s[46:47]
	v_mov_b32_e32 v250, 0x1c00
	global_atomic_add v250, v251, s[46:47]
	s_waitcnt vmcnt(0)

.Lp7_pull:
	s_waitcnt lgkmcnt(0)
	s_barrier
	s_and_saveexec_b64 s[100:101], s[44:45]
	s_cbranch_execz .Lp7_got
	v_mov_b32_e32 v250, 0x400
	v_mov_b32_e32 v251, 1
	global_atomic_add v250, v250, v251, s[46:47] sc0
	v_mov_b32_e32 v251, 0x1c00
	global_load_dword v251, v251, s[46:47] sc1
	s_waitcnt vmcnt(0)
	v_cmp_lt_u32_e32 vcc, 63, v251
	s_nop 1
	v_cndmask_b32_e64 v251, 0, 1, vcc
	v_lshl_or_b32 v250, v251, 16, v250
	v_mov_b32_e32 v251, 0x24184
	ds_write_b32 v251, v250
	s_waitcnt lgkmcnt(0)
.Lp7_got:
	s_or_b64 exec, exec, s[100:101]
	s_barrier
	v_mov_b32_e32 v251, 0x24184
	ds_read_b32 v250, v251
	s_waitcnt lgkmcnt(0)
	s_nop 0
	v_readfirstlane_b32 s98, v250
	s_nop 0
	s_and_b32 s98, s98, 0xffff
	s_cmp_ge_u32 s98, 0x100
	s_cbranch_scc1 .Lp7_done
	s_mov_b32 s54, s98
	s_lshr_b32 s100, s54, 5
	s_lshl_b32 s100, s100, 3
	s_and_b32 s101, s54, 7
	s_add_i32 s100, s100, s101
	s_lshr_b32 s100, s100, 4
	s_lshl_b32 s100, s100, 2
	s_bfe_u32 s101, s54, 0x20003
	s_add_i32 s100, s100, s101
	s_lshl_b32 s100, s100, 8
	s_add_i32 s100, s100, 0x800
	v_mov_b32_e32 v251, s100
	s_and_saveexec_b64 s[100:101], s[44:45]
	s_cbranch_execz .Lp7_ready
	v_cmp_lt_u32_e32 vcc, 0xffff, v250
	s_cbranch_vccnz .Lp7_acq
	s_mov_b32 s98, 0
